# baseline (speedup 1.0000x reference)
; __device__ __forceinline__ unsigned xb_ld(unsigned* p)              { return __hip_atomic_load(p, __ATOMIC_RELAXED, __HIP_MEMORY_SCOPE_AGENT); }
; __device__ __forceinline__ unsigned xb_add(unsigned* p, unsigned v) { return __hip_atomic_fetch_add(p, v, __ATOMIC_RELAXED, __HIP_MEMORY_SCOPE_AGENT); }
; #define XB_SPIN(cond, bar) do { unsigned _sp = 0; while (cond) { __builtin_amdgcn_s_sleep(1); \
;     if ((++_sp & 255u) == 0u) { if (xb_ld(&(bar)[XB_TMO])) break; if (_sp > XB_SPIN_CAP) { atomicAdd(&(bar)[XB_TMO], 1u); break; } } } } while (0)
; __device__ __forceinline__ void xcd_barrier(const XcdBarrier& b) {
;     ...
;     const unsigned old = xb_add(&bar[XB_XSUB(b.x)], 1u);
;     const unsigned gen = old / nloc;
;     if (old + 1u == (gen + 1u) * nloc) {
;       __builtin_amdgcn_fence(__ATOMIC_RELEASE, "agent");
;       asm volatile("s_waitcnt vmcnt(0)" ::: "memory");
;       const unsigned og = xb_add(&bar[XB_TOP], 1u);
;       const unsigned tg = og / nx;
;       if (og + 1u == (tg + 1u) * nx) xb_add(&bar[XB_TOPGEN], 1u);
;       else XB_SPIN(xb_ld(&bar[XB_TOPGEN]) == tg, bar);
;       __builtin_amdgcn_fence(__ATOMIC_ACQUIRE, "agent");
;       xb_add(&bar[XB_XGEN(b.x)], 1u);
;       asm volatile("s_waitcnt vmcnt(0)" ::: "memory");
;     } else {
;       XB_SPIN(xb_ld(&bar[XB_XGEN(b.x)]) == gen, bar);
.LBB0_842:
	s_or_b64 exec, exec, s[38:39]
	v_cvt_f32_u32_e32 v4, v2
	s_waitcnt vmcnt(0)
	v_readfirstlane_b32 s4, v3
	v_sub_u32_e32 v3, 0, v2
	v_rcp_iflag_f32_e32 v4, v4
	v_add_u32_e32 v5, s4, v1
	v_mul_f32_e32 v4, 0x4f7ffffe, v4
	v_cvt_u32_f32_e32 v4, v4
	v_mul_lo_u32 v1, v3, v4
	v_mul_hi_u32 v1, v4, v1
	v_add_u32_e32 v1, v4, v1
	v_mul_hi_u32 v1, v5, v1
	v_mul_lo_u32 v3, v1, v2
	v_sub_u32_e32 v3, v5, v3
	v_add_u32_e32 v4, 1, v1
	v_cmp_ge_u32_e32 vcc, v3, v2
	s_nop 1
	v_cndmask_b32_e32 v1, v1, v4, vcc
	v_sub_u32_e32 v4, v3, v2
	v_cndmask_b32_e32 v3, v3, v4, vcc
	v_add_u32_e32 v4, 1, v1
	v_cmp_ge_u32_e32 vcc, v3, v2
	v_add_u32_e32 v3, 1, v5
	s_nop 0
	v_cndmask_b32_e32 v1, v1, v4, vcc
	v_mul_lo_u32 v4, v2, v1
	v_add_u32_e32 v2, v4, v2
	v_cmp_ne_u32_e32 vcc, v3, v2
	s_and_saveexec_b64 s[38:39], vcc
	s_xor_b64 s[38:39], exec, s[38:39]
	s_cbranch_execz .LBB0_856
	v_readlane_b32 s4, v251, 28
	v_readlane_b32 s5, v251, 29
	s_waitcnt lgkmcnt(0)
	v_add_u32_e32 v4, 1, v1
	v_mul_lo_u32 v4, v4, v0
	s_nop 3
	global_load_dword v0, v177, s[4:5] sc1
	s_waitcnt vmcnt(0)
	v_cmp_lt_u32_e32 vcc, v0, v4
	s_and_saveexec_b64 s[40:41], vcc
	s_cbranch_execz .LBB0_855
	s_mov_b32 s11, 1
	s_mov_b64 s[42:43], 0
	s_branch .LBB0_846

.LBB0_851:
	s_cmp_lt_u32 s11, 0x2001
	s_mov_b64 s[90:91], 0
	s_cselect_b64 vcc, -1, 0
	s_and_b64 vcc, exec, vcc
	s_cbranch_vccz .LBB0_845
	s_branch .LBB0_850
.LBB0_852:
	s_or_b64 exec, exec, s[42:43]
	s_xor_b64 s[42:43], s[86:87], -1
	s_and_saveexec_b64 s[66:67], s[42:43]
	s_xor_b64 s[66:67], exec, s[66:67]
	s_cbranch_execz .LBB0_855
	s_mov_b64 s[42:43], exec
	v_mbcnt_lo_u32_b32 v0, s42, 0
	v_mbcnt_hi_u32_b32 v0, s43, v0
	v_cmp_eq_u32_e32 vcc, 0, v0
	s_and_b64 s[66:67], exec, vcc
	s_mov_b64 exec, s[66:67]
	s_cbranch_execz .LBB0_855
	s_bcnt1_i32_b64 s4, s[42:43]
	v_mov_b32_e32 v0, s4
	global_atomic_add v177, v0, s[76:77]

; __device__ __forceinline__ unsigned xb_add(unsigned* p, unsigned v) { return __hip_atomic_fetch_add(p, v, __ATOMIC_RELAXED, __HIP_MEMORY_SCOPE_AGENT); }
; __device__ __forceinline__ void xcd_barrier(const XcdBarrier& b) {
;     ...
;     if (old + 1u == (gen + 1u) * nloc) {
;       __builtin_amdgcn_fence(__ATOMIC_RELEASE, "agent");
;       asm volatile("s_waitcnt vmcnt(0)" ::: "memory");
;       const unsigned og = xb_add(&bar[XB_TOP], 1u);
.LBB0_856:
	s_andn2_saveexec_b64 s[38:39], s[38:39]
	s_cbranch_execz .LBB0_876
	s_mov_b64 s[38:39], exec
	buffer_wbl2 sc1
	s_waitcnt lgkmcnt(0)
	s_waitcnt vmcnt(0)
	buffer_inv sc1
	s_waitcnt vmcnt(0)
	v_mbcnt_lo_u32_b32 v1, s38, 0
	v_mbcnt_hi_u32_b32 v1, s39, v1
	v_cmp_eq_u32_e32 vcc, 0, v1
	s_and_saveexec_b64 s[40:41], vcc
	s_cbranch_execz .LBB0_859
	s_bcnt1_i32_b64 s4, s[38:39]
	v_mov_b32_e32 v2, s4
	v_readlane_b32 s4, v251, 28
	v_readlane_b32 s5, v251, 29
	s_nop 4
	global_atomic_add v2, v177, v2, s[4:5] sc0

; __device__ __forceinline__ unsigned xb_add(unsigned* p, unsigned v) { return __hip_atomic_fetch_add(p, v, __ATOMIC_RELAXED, __HIP_MEMORY_SCOPE_AGENT); }
; __device__ __forceinline__ void xcd_barrier(const XcdBarrier& b) {
;     ...
;       __builtin_amdgcn_fence(__ATOMIC_ACQUIRE, "agent");
;       xb_add(&bar[XB_XGEN(b.x)], 1u);
;       asm volatile("s_waitcnt vmcnt(0)" ::: "memory");
.LBB0_873:
	s_or_b64 exec, exec, s[38:39]
	s_mov_b64 s[38:39], exec
	v_mbcnt_lo_u32_b32 v0, s38, 0
	v_mbcnt_hi_u32_b32 v0, s39, v0
	v_cmp_eq_u32_e32 vcc, 0, v0
	s_waitcnt vmcnt(0)
	buffer_inv sc0
	s_and_saveexec_b64 s[40:41], vcc
	s_cbranch_execz .LBB0_875
	s_bcnt1_i32_b64 s4, s[38:39]
	v_mov_b32_e32 v0, s4
	v_readlane_b32 s4, v251, 26
	v_readlane_b32 s5, v251, 27
	s_nop 4
	s_nop 0

; __device__ __forceinline__ unsigned xb_ld(unsigned* p)              { return __hip_atomic_load(p, __ATOMIC_RELAXED, __HIP_MEMORY_SCOPE_AGENT); }
; __device__ __forceinline__ unsigned xb_add(unsigned* p, unsigned v) { return __hip_atomic_fetch_add(p, v, __ATOMIC_RELAXED, __HIP_MEMORY_SCOPE_AGENT); }
; #define XB_SPIN(cond, bar) do { unsigned _sp = 0; while (cond) { __builtin_amdgcn_s_sleep(1); \
;     if ((++_sp & 255u) == 0u) { if (xb_ld(&(bar)[XB_TMO])) break; if (_sp > XB_SPIN_CAP) { atomicAdd(&(bar)[XB_TMO], 1u); break; } } } } while (0)
; __device__ __forceinline__ void xcd_barrier(const XcdBarrier& b) {
;     ...
;     const unsigned old = xb_add(&bar[XB_XSUB(b.x)], 1u);
;     const unsigned gen = old / nloc;
;     if (old + 1u == (gen + 1u) * nloc) {
;       __builtin_amdgcn_fence(__ATOMIC_RELEASE, "agent");
;       asm volatile("s_waitcnt vmcnt(0)" ::: "memory");
;       const unsigned og = xb_add(&bar[XB_TOP], 1u);
;       const unsigned tg = og / nx;
;       if (og + 1u == (tg + 1u) * nx) xb_add(&bar[XB_TOPGEN], 1u);
;       else XB_SPIN(xb_ld(&bar[XB_TOPGEN]) == tg, bar);
;       __builtin_amdgcn_fence(__ATOMIC_ACQUIRE, "agent");
;       xb_add(&bar[XB_XGEN(b.x)], 1u);
;       asm volatile("s_waitcnt vmcnt(0)" ::: "memory");
;     } else {
;       XB_SPIN(xb_ld(&bar[XB_XGEN(b.x)]) == gen, bar);
.LBB0_917:
	s_or_b64 exec, exec, s[2:3]
	v_cvt_f32_u32_e32 v4, v2
	s_waitcnt vmcnt(0)
	v_readfirstlane_b32 s2, v3
	v_sub_u32_e32 v3, 0, v2
	v_rcp_iflag_f32_e32 v4, v4
	v_add_u32_e32 v5, s2, v1
	v_mul_f32_e32 v4, 0x4f7ffffe, v4
	v_cvt_u32_f32_e32 v4, v4
	v_mul_lo_u32 v1, v3, v4
	v_mul_hi_u32 v1, v4, v1
	v_add_u32_e32 v1, v4, v1
	v_mul_hi_u32 v1, v5, v1
	v_mul_lo_u32 v3, v1, v2
	v_sub_u32_e32 v3, v5, v3
	v_add_u32_e32 v4, 1, v1
	v_cmp_ge_u32_e32 vcc, v3, v2
	s_nop 1
	v_cndmask_b32_e32 v1, v1, v4, vcc
	v_sub_u32_e32 v4, v3, v2
	v_cndmask_b32_e32 v3, v3, v4, vcc
	v_add_u32_e32 v4, 1, v1
	v_cmp_ge_u32_e32 vcc, v3, v2
	v_add_u32_e32 v3, 1, v5
	s_nop 0
	v_cndmask_b32_e32 v1, v1, v4, vcc
	v_mul_lo_u32 v4, v2, v1
	v_add_u32_e32 v2, v4, v2
	v_cmp_ne_u32_e32 vcc, v3, v2
	s_and_saveexec_b64 s[2:3], vcc
	s_xor_b64 s[2:3], exec, s[2:3]
	s_cbranch_execz .LBB0_931
	v_readlane_b32 s4, v251, 28
	v_readlane_b32 s5, v251, 29
	s_waitcnt lgkmcnt(0)
	v_add_u32_e32 v4, 1, v1
	v_mul_lo_u32 v4, v4, v0
	s_nop 3
	global_load_dword v0, v177, s[4:5] sc1
	s_waitcnt vmcnt(0)
	v_cmp_lt_u32_e32 vcc, v0, v4
	s_and_saveexec_b64 s[38:39], vcc
	s_cbranch_execz .LBB0_930
	s_mov_b32 s11, 1
	s_mov_b64 s[40:41], 0
	s_branch .LBB0_921

.LBB0_926:
	s_cmp_lt_u32 s11, 0x2001
	s_mov_b64 s[88:89], 0
	s_cselect_b64 s[90:91], -1, 0
	s_and_b64 vcc, exec, s[90:91]
	s_cbranch_vccz .LBB0_920
	s_branch .LBB0_925
.LBB0_927:
	s_or_b64 exec, exec, s[40:41]
	s_xor_b64 s[40:41], s[42:43], -1
	s_and_saveexec_b64 s[42:43], s[40:41]
	v_readlane_b32 s78, v250, 0
	v_readlane_b32 s86, v250, 2
	v_readlane_b32 s90, v250, 4
	v_readlane_b32 s79, v250, 1
	v_readlane_b32 s87, v250, 3
	v_readlane_b32 s91, v250, 5
	s_xor_b64 s[42:43], exec, s[42:43]
	s_cbranch_execz .LBB0_930
	s_mov_b64 s[40:41], exec
	v_mbcnt_lo_u32_b32 v0, s40, 0
	v_mbcnt_hi_u32_b32 v0, s41, v0
	v_cmp_eq_u32_e32 vcc, 0, v0
	s_and_b64 s[42:43], exec, vcc
	s_mov_b64 exec, s[42:43]
	s_cbranch_execz .LBB0_930
	s_bcnt1_i32_b64 s4, s[40:41]
	v_mov_b32_e32 v0, s4
	global_atomic_add v177, v0, s[76:77]

; __device__ __forceinline__ unsigned xb_add(unsigned* p, unsigned v) { return __hip_atomic_fetch_add(p, v, __ATOMIC_RELAXED, __HIP_MEMORY_SCOPE_AGENT); }
; __device__ __forceinline__ void xcd_barrier(const XcdBarrier& b) {
;     ...
;     if (old + 1u == (gen + 1u) * nloc) {
;       __builtin_amdgcn_fence(__ATOMIC_RELEASE, "agent");
;       asm volatile("s_waitcnt vmcnt(0)" ::: "memory");
;       const unsigned og = xb_add(&bar[XB_TOP], 1u);
.LBB0_931:
	s_andn2_saveexec_b64 s[2:3], s[2:3]
	s_cbranch_execz .LBB0_951
	s_mov_b64 s[2:3], exec
	buffer_wbl2 sc1
	s_waitcnt lgkmcnt(0)
	s_waitcnt vmcnt(0)
	buffer_inv sc1
	s_waitcnt vmcnt(0)
	v_mbcnt_lo_u32_b32 v1, s2, 0
	v_mbcnt_hi_u32_b32 v1, s3, v1
	v_cmp_eq_u32_e32 vcc, 0, v1
	s_and_saveexec_b64 s[38:39], vcc
	s_cbranch_execz .LBB0_934
	s_bcnt1_i32_b64 s2, s[2:3]
	v_mov_b32_e32 v2, s2
	v_readlane_b32 s2, v251, 28
	v_readlane_b32 s3, v251, 29
	s_nop 4
	global_atomic_add v2, v177, v2, s[2:3] sc0

; __device__ __forceinline__ unsigned xb_add(unsigned* p, unsigned v) { return __hip_atomic_fetch_add(p, v, __ATOMIC_RELAXED, __HIP_MEMORY_SCOPE_AGENT); }
; __device__ __forceinline__ void xcd_barrier(const XcdBarrier& b) {
;     ...
;       __builtin_amdgcn_fence(__ATOMIC_ACQUIRE, "agent");
;       xb_add(&bar[XB_XGEN(b.x)], 1u);
;       asm volatile("s_waitcnt vmcnt(0)" ::: "memory");
.LBB0_948:
	s_or_b64 exec, exec, s[2:3]
	s_mov_b64 s[2:3], exec
	v_mbcnt_lo_u32_b32 v0, s2, 0
	v_mbcnt_hi_u32_b32 v0, s3, v0
	v_cmp_eq_u32_e32 vcc, 0, v0
	s_waitcnt vmcnt(0)
	buffer_inv sc0
	s_and_saveexec_b64 s[38:39], vcc
	s_cbranch_execz .LBB0_950
	s_bcnt1_i32_b64 s2, s[2:3]
	v_mov_b32_e32 v0, s2
	v_readlane_b32 s2, v251, 26
	v_readlane_b32 s3, v251, 27
	s_nop 4
	s_nop 0

.LBB0_983:
	s_cmp_lt_u32 s11, 0x2001
	s_mov_b64 s[88:89], 0
	s_cselect_b64 s[90:91], -1, 0
	s_and_b64 vcc, exec, s[90:91]
	s_cbranch_vccz .LBB0_977
	s_branch .LBB0_982
.LBB0_984:
	s_or_b64 exec, exec, s[40:41]
	s_xor_b64 s[40:41], s[42:43], -1
	s_and_saveexec_b64 s[42:43], s[40:41]
	v_readlane_b32 s78, v250, 0
	v_readlane_b32 s86, v250, 2
	v_readlane_b32 s90, v250, 4
	v_readlane_b32 s79, v250, 1
	v_readlane_b32 s87, v250, 3
	v_readlane_b32 s91, v250, 5
	s_xor_b64 s[42:43], exec, s[42:43]
	s_cbranch_execz .LBB0_987
	s_mov_b64 s[40:41], exec
	v_mbcnt_lo_u32_b32 v0, s40, 0
	v_mbcnt_hi_u32_b32 v0, s41, v0
	v_cmp_eq_u32_e32 vcc, 0, v0
	s_and_b64 s[42:43], exec, vcc
	s_mov_b64 exec, s[42:43]
	s_cbranch_execz .LBB0_987
	s_bcnt1_i32_b64 s4, s[40:41]
	v_mov_b32_e32 v0, s4
	global_atomic_add v177, v0, s[76:77]

.LBB0_1039:
	s_cmp_lt_u32 s11, 0x2001
	s_mov_b64 s[88:89], 0
	s_cselect_b64 s[90:91], -1, 0
	s_and_b64 vcc, exec, s[90:91]
	s_cbranch_vccz .LBB0_1033
	s_branch .LBB0_1038
.LBB0_1040:
	s_or_b64 exec, exec, s[40:41]
	s_xor_b64 s[40:41], s[42:43], -1
	s_and_saveexec_b64 s[42:43], s[40:41]
	v_readlane_b32 s78, v250, 0
	v_readlane_b32 s86, v250, 2
	v_readlane_b32 s90, v250, 4
	v_readlane_b32 s79, v250, 1
	v_readlane_b32 s87, v250, 3
	v_readlane_b32 s91, v250, 5
	s_xor_b64 s[42:43], exec, s[42:43]
	s_cbranch_execz .LBB0_1043
	s_mov_b64 s[40:41], exec
	v_mbcnt_lo_u32_b32 v0, s40, 0
	v_mbcnt_hi_u32_b32 v0, s41, v0
	v_cmp_eq_u32_e32 vcc, 0, v0
	s_and_b64 s[42:43], exec, vcc
	s_mov_b64 exec, s[42:43]
	s_cbranch_execz .LBB0_1043
	s_bcnt1_i32_b64 s4, s[40:41]
	v_mov_b32_e32 v0, s4
	global_atomic_add v177, v0, s[76:77]

; __device__ __forceinline__ unsigned xb_ld(unsigned* p)              { return __hip_atomic_load(p, __ATOMIC_RELAXED, __HIP_MEMORY_SCOPE_AGENT); }
; __device__ __forceinline__ unsigned xb_add(unsigned* p, unsigned v) { return __hip_atomic_fetch_add(p, v, __ATOMIC_RELAXED, __HIP_MEMORY_SCOPE_AGENT); }
; #define XB_SPIN(cond, bar) do { unsigned _sp = 0; while (cond) { __builtin_amdgcn_s_sleep(1); \
;     if ((++_sp & 255u) == 0u) { if (xb_ld(&(bar)[XB_TMO])) break; if (_sp > XB_SPIN_CAP) { atomicAdd(&(bar)[XB_TMO], 1u); break; } } } } while (0)
; __device__ __forceinline__ void xcd_barrier(const XcdBarrier& b) {
;     ...
;     const unsigned old = xb_add(&bar[XB_XSUB(b.x)], 1u);
;     const unsigned gen = old / nloc;
;     if (old + 1u == (gen + 1u) * nloc) {
;       __builtin_amdgcn_fence(__ATOMIC_RELEASE, "agent");
;       asm volatile("s_waitcnt vmcnt(0)" ::: "memory");
;       const unsigned og = xb_add(&bar[XB_TOP], 1u);
;       const unsigned tg = og / nx;
;       if (og + 1u == (tg + 1u) * nx) xb_add(&bar[XB_TOPGEN], 1u);
;       else XB_SPIN(xb_ld(&bar[XB_TOPGEN]) == tg, bar);
;       __builtin_amdgcn_fence(__ATOMIC_ACQUIRE, "agent");
;       xb_add(&bar[XB_XGEN(b.x)], 1u);
;       asm volatile("s_waitcnt vmcnt(0)" ::: "memory");
;     } else {
;       XB_SPIN(xb_ld(&bar[XB_XGEN(b.x)]) == gen, bar);
.LBB0_1098:
	s_or_b64 exec, exec, s[38:39]
	v_cvt_f32_u32_e32 v4, v2
	s_waitcnt vmcnt(0)
	v_readfirstlane_b32 s2, v3
	v_sub_u32_e32 v3, 0, v2
	v_rcp_iflag_f32_e32 v4, v4
	v_add_u32_e32 v5, s2, v1
	v_mul_f32_e32 v4, 0x4f7ffffe, v4
	v_cvt_u32_f32_e32 v4, v4
	v_mul_lo_u32 v1, v3, v4
	v_mul_hi_u32 v1, v4, v1
	v_add_u32_e32 v1, v4, v1
	v_mul_hi_u32 v1, v5, v1
	v_mul_lo_u32 v3, v1, v2
	v_sub_u32_e32 v3, v5, v3
	v_add_u32_e32 v4, 1, v1
	v_cmp_ge_u32_e32 vcc, v3, v2
	s_nop 1
	v_cndmask_b32_e32 v1, v1, v4, vcc
	v_sub_u32_e32 v4, v3, v2
	v_cndmask_b32_e32 v3, v3, v4, vcc
	v_add_u32_e32 v4, 1, v1
	v_cmp_ge_u32_e32 vcc, v3, v2
	v_add_u32_e32 v3, 1, v5
	s_nop 0
	v_cndmask_b32_e32 v1, v1, v4, vcc
	v_mul_lo_u32 v4, v2, v1
	v_add_u32_e32 v2, v4, v2
	v_cmp_ne_u32_e32 vcc, v3, v2
	s_and_saveexec_b64 s[2:3], vcc
	s_xor_b64 s[38:39], exec, s[2:3]
	s_cbranch_execz .LBB0_1112
	v_readlane_b32 s2, v251, 28
	v_readlane_b32 s3, v251, 29
	s_waitcnt lgkmcnt(0)
	v_add_u32_e32 v4, 1, v1
	v_mul_lo_u32 v4, v4, v0
	s_nop 3
	global_load_dword v0, v177, s[2:3] sc1
	s_waitcnt vmcnt(0)
	v_cmp_lt_u32_e32 vcc, v0, v4
	s_and_saveexec_b64 s[40:41], vcc
	s_cbranch_execz .LBB0_1111
	s_mov_b32 s2, 1
	s_mov_b64 s[42:43], 0
	s_branch .LBB0_1102

.LBB0_1107:
	s_cmp_lt_u32 s2, 0x2001
	s_mov_b64 s[90:91], 0
	s_cselect_b64 vcc, -1, 0
	s_and_b64 vcc, exec, vcc
	s_cbranch_vccz .LBB0_1101
	s_branch .LBB0_1106
.LBB0_1108:
	s_or_b64 exec, exec, s[42:43]
	s_xor_b64 s[2:3], s[86:87], -1
	s_and_saveexec_b64 s[42:43], s[2:3]
	v_readlane_b32 s78, v250, 0
	v_readlane_b32 s86, v250, 2
	v_readlane_b32 s90, v250, 4
	v_readlane_b32 s79, v250, 1
	v_readlane_b32 s87, v250, 3
	v_readlane_b32 s91, v250, 5
	s_xor_b64 s[42:43], exec, s[42:43]
	s_cbranch_execz .LBB0_1111
	s_mov_b64 s[42:43], exec
	v_mbcnt_lo_u32_b32 v0, s42, 0
	v_mbcnt_hi_u32_b32 v0, s43, v0
	v_cmp_eq_u32_e32 vcc, 0, v0
	s_and_b64 s[2:3], exec, vcc
	s_mov_b64 exec, s[2:3]
	s_cbranch_execz .LBB0_1111
	s_bcnt1_i32_b64 s2, s[42:43]
	v_mov_b32_e32 v0, s2
	global_atomic_add v177, v0, s[76:77]

; __device__ __forceinline__ unsigned xb_add(unsigned* p, unsigned v) { return __hip_atomic_fetch_add(p, v, __ATOMIC_RELAXED, __HIP_MEMORY_SCOPE_AGENT); }
; __device__ __forceinline__ void xcd_barrier(const XcdBarrier& b) {
;     ...
;     if (old + 1u == (gen + 1u) * nloc) {
;       __builtin_amdgcn_fence(__ATOMIC_RELEASE, "agent");
;       asm volatile("s_waitcnt vmcnt(0)" ::: "memory");
;       const unsigned og = xb_add(&bar[XB_TOP], 1u);
.LBB0_1112:
	s_andn2_saveexec_b64 s[2:3], s[38:39]
	s_cbranch_execz .LBB0_1132
	s_mov_b64 s[38:39], exec
	buffer_wbl2 sc1
	s_waitcnt lgkmcnt(0)
	s_waitcnt vmcnt(0)
	buffer_inv sc1
	s_waitcnt vmcnt(0)
	v_mbcnt_lo_u32_b32 v1, s38, 0
	v_mbcnt_hi_u32_b32 v1, s39, v1
	v_cmp_eq_u32_e32 vcc, 0, v1
	s_and_saveexec_b64 s[40:41], vcc
	s_cbranch_execz .LBB0_1115
	s_bcnt1_i32_b64 s2, s[38:39]
	v_mov_b32_e32 v2, s2
	v_readlane_b32 s2, v251, 28
	v_readlane_b32 s3, v251, 29
	s_nop 4
	global_atomic_add v2, v177, v2, s[2:3] sc0

; __device__ __forceinline__ unsigned xb_add(unsigned* p, unsigned v) { return __hip_atomic_fetch_add(p, v, __ATOMIC_RELAXED, __HIP_MEMORY_SCOPE_AGENT); }
; __device__ __forceinline__ void xcd_barrier(const XcdBarrier& b) {
;     ...
;       __builtin_amdgcn_fence(__ATOMIC_ACQUIRE, "agent");
;       xb_add(&bar[XB_XGEN(b.x)], 1u);
;       asm volatile("s_waitcnt vmcnt(0)" ::: "memory");
.LBB0_1129:
	s_or_b64 exec, exec, s[38:39]
	s_mov_b64 s[38:39], exec
	v_mbcnt_lo_u32_b32 v0, s38, 0
	v_mbcnt_hi_u32_b32 v0, s39, v0
	v_cmp_eq_u32_e32 vcc, 0, v0
	s_waitcnt vmcnt(0)
	buffer_inv sc0
	s_and_saveexec_b64 s[40:41], vcc
	s_cbranch_execz .LBB0_1131
	s_bcnt1_i32_b64 s2, s[38:39]
	v_mov_b32_e32 v0, s2
	v_readlane_b32 s2, v251, 26
	v_readlane_b32 s3, v251, 27
	s_nop 4
	s_nop 0

.LBB0_1162:
	s_cmp_lt_u32 s2, 0x2001
	s_mov_b64 s[90:91], 0
	s_cselect_b64 vcc, -1, 0
	s_and_b64 vcc, exec, vcc
	s_cbranch_vccz .LBB0_1156
	s_branch .LBB0_1161
.LBB0_1163:
	s_or_b64 exec, exec, s[42:43]
	s_xor_b64 s[2:3], s[86:87], -1
	s_and_saveexec_b64 s[42:43], s[2:3]
	v_readlane_b32 s78, v250, 0
	v_readlane_b32 s86, v250, 2
	v_readlane_b32 s90, v250, 4
	v_readlane_b32 s79, v250, 1
	v_readlane_b32 s87, v250, 3
	v_readlane_b32 s91, v250, 5
	s_xor_b64 s[42:43], exec, s[42:43]
	s_cbranch_execz .LBB0_1166
	s_mov_b64 s[42:43], exec
	v_mbcnt_lo_u32_b32 v0, s42, 0
	v_mbcnt_hi_u32_b32 v0, s43, v0
	v_cmp_eq_u32_e32 vcc, 0, v0
	s_and_b64 s[2:3], exec, vcc
	s_mov_b64 exec, s[2:3]
	s_cbranch_execz .LBB0_1166
	s_bcnt1_i32_b64 s2, s[42:43]
	v_mov_b32_e32 v0, s2
	global_atomic_add v177, v0, s[76:77]

.LBB0_1230:
	s_cmp_lt_u32 s11, 0x2001
	s_mov_b64 s[88:89], 0
	s_cselect_b64 s[90:91], -1, 0
	s_and_b64 vcc, exec, s[90:91]
	s_cbranch_vccz .LBB0_1224
	s_branch .LBB0_1229
.LBB0_1231:
	s_or_b64 exec, exec, s[40:41]
	s_xor_b64 s[40:41], s[42:43], -1
	s_and_saveexec_b64 s[42:43], s[40:41]
	s_xor_b64 s[42:43], exec, s[42:43]
	s_cbranch_execz .LBB0_1234
	s_mov_b64 s[40:41], exec
	v_mbcnt_lo_u32_b32 v0, s40, 0
	v_mbcnt_hi_u32_b32 v0, s41, v0
	v_cmp_eq_u32_e32 vcc, 0, v0
	s_and_b64 s[42:43], exec, vcc
	s_mov_b64 exec, s[42:43]
	s_cbranch_execz .LBB0_1234
	s_bcnt1_i32_b64 s4, s[40:41]
	v_mov_b32_e32 v0, s4
	global_atomic_add v177, v0, s[76:77]

.LBB0_1297:
	s_cmp_lt_u32 s11, 0x2001
	s_mov_b64 s[86:87], 0
	s_cselect_b64 s[88:89], -1, 0
	s_and_b64 vcc, exec, s[88:89]
	s_cbranch_vccz .LBB0_1291
	s_branch .LBB0_1296
.LBB0_1298:
	s_or_b64 exec, exec, s[40:41]
	s_xor_b64 s[40:41], s[42:43], -1
	s_and_saveexec_b64 s[42:43], s[40:41]
	v_readlane_b32 s76, v251, 60
	v_readlane_b32 s77, v251, 61
	s_xor_b64 s[42:43], exec, s[42:43]
	s_cbranch_execz .LBB0_1301
	s_mov_b64 s[40:41], exec
	v_mbcnt_lo_u32_b32 v0, s40, 0
	v_mbcnt_hi_u32_b32 v0, s41, v0
	v_cmp_eq_u32_e32 vcc, 0, v0
	s_and_b64 s[42:43], exec, vcc
	s_mov_b64 exec, s[42:43]
	s_cbranch_execz .LBB0_1301
	s_bcnt1_i32_b64 s4, s[40:41]
	v_mov_b32_e32 v0, s4
	global_atomic_add v177, v0, s[76:77]

; __device__ __forceinline__ unsigned xb_add(unsigned* p, unsigned v) { return __hip_atomic_fetch_add(p, v, __ATOMIC_RELAXED, __HIP_MEMORY_SCOPE_AGENT); }
; __device__ __forceinline__ void xcd_barrier(const XcdBarrier& b) {
;     ...
;       __builtin_amdgcn_fence(__ATOMIC_ACQUIRE, "agent");
;       xb_add(&bar[XB_XGEN(b.x)], 1u);
;       asm volatile("s_waitcnt vmcnt(0)" ::: "memory");
.LBB0_1319:
	s_or_b64 exec, exec, s[2:3]
	s_mov_b64 s[2:3], exec
	v_mbcnt_lo_u32_b32 v0, s2, 0
	v_mbcnt_hi_u32_b32 v0, s3, v0
	v_cmp_eq_u32_e32 vcc, 0, v0
	s_waitcnt vmcnt(0)
	buffer_inv sc0
	s_and_saveexec_b64 s[38:39], vcc
	s_cbranch_execz .LBB0_810
	s_bcnt1_i32_b64 s2, s[2:3]
	v_mov_b32_e32 v0, s2
	v_readlane_b32 s2, v251, 26
	v_readlane_b32 s3, v251, 27
	s_nop 4
	s_nop 0
	s_branch .LBB0_810
